# hyena conv steps: first five steps of the filter-norm wave_sum done with v_permlane32/16_swap and DPP row_mirror/half_mirror/quad_perm instead of serialized ds_bpermute round trips
# speedup vs baseline: 1.0024x; 1.0024x over previous
.LBB0_720:
	ds_write_b128 v28, v[2:5] offset:32800
	s_and_saveexec_b64 s[50:51], s[44:45]
	ds_write_b128 v28, v[6:9] offset:33824
	s_or_b64 exec, exec, s[50:51]
	v_mov_b32_e32 v14, v124
	v_mov_b32_e32 v15, v124
	s_nop 1
	v_permlane32_swap_b32_e32 v14, v15
	s_lshl_b32 s53, s52, 1
	v_add_u32_e32 v26, s53, v111
	v_add_u32_e32 v20, s16, v26
	v_mad_i64_i32 v[18:19], s[50:51], v20, s9, v[22:23]
	s_waitcnt lgkmcnt(0)
	v_add_f32_e32 v14, v14, v15
	v_mov_b32_e32 v15, v14
	s_nop 1
	v_permlane16_swap_b32_e32 v15, v14
	s_waitcnt lgkmcnt(0)
	v_add_f32_e32 v14, v14, v15
	s_nop 1
	v_mov_b32_dpp v15, v14 row_mirror row_mask:0xf bank_mask:0xf
	s_waitcnt lgkmcnt(0)
	v_add_f32_e32 v14, v14, v15
	s_nop 1
	v_mov_b32_dpp v15, v14 row_half_mirror row_mask:0xf bank_mask:0xf
	s_waitcnt lgkmcnt(0)
	v_add_f32_e32 v14, v14, v15
	s_nop 1
	v_mov_b32_dpp v15, v14 quad_perm:[2,3,0,1] row_mask:0xf bank_mask:0xf
	s_waitcnt lgkmcnt(0)
	v_add_f32_e32 v42, v14, v15
	global_load_dwordx4 v[14:17], v[18:19], off
	ds_bpermute_b32 v43, v34, v42
	s_and_saveexec_b64 s[50:51], s[44:45]
	s_cbranch_execz .LBB0_724
	global_load_dwordx4 v[10:13], v[18:19], off offset:1024

.LBB0_726:
	s_or_b64 exec, exec, s[50:51]
	v_ashrrev_i32_e32 v21, 31, v20
	v_lshl_add_u64 v[20:21], v[20:21], 2, s[26:27]
	global_load_dword v24, v[20:21], off
	s_movk_i32 s50, 0xfee0
	v_mov_b32_e32 v44, v41
	v_mov_b32_e32 v19, v18
	v_mov_b32_e32 v20, v18
	v_mov_b32_e32 v21, v18
	v_mov_b32_e32 v156, v44
	v_add_lshl_u32 v155, v35, s50, 1
	v_and_b32_e32 v155, -4, v155
	v_add_u32_e32 v155, v25, v155
	v_add_u32_e32 v154, 0x8260, v155
	ds_read_b128 v[236:239], v156
	ds_read2_b32 v[204:205], v154 offset1:1
	ds_read2_b32 v[206:207], v154 offset0:2 offset1:3
	ds_read_b32 v208, v154 offset:16
	ds_read_b128 v[240:243], v156 offset:64
	ds_read2_b32 v[210:211], v154 offset0:16 offset1:17
	ds_read2_b32 v[212:213], v154 offset0:18 offset1:19
	ds_read_b32 v214, v154 offset:80
	ds_read_b128 v[244:247], v156 offset:128
	ds_read2_b32 v[216:217], v154 offset0:32 offset1:33
	ds_read2_b32 v[218:219], v154 offset0:34 offset1:35
	ds_read_b32 v220, v154 offset:144
	ds_read_b128 v[144:147], v156 offset:192
	ds_read2_b32 v[222:223], v154 offset0:48 offset1:49
	ds_read2_b32 v[224:225], v154 offset0:50 offset1:51
	ds_read_b32 v226, v154 offset:208
	s_waitcnt lgkmcnt(12)
	v_alignbyte_b32 v228, v205, v204, v36
	v_alignbyte_b32 v229, v206, v205, v36
	v_alignbyte_b32 v230, v207, v206, v36
	v_alignbyte_b32 v231, v208, v207, v36
	ds_read2_b32 v[204:205], v154 offset0:64 offset1:65
	ds_read2_b32 v[206:207], v154 offset0:66 offset1:67
	ds_read_b32 v208, v154 offset:272
	v_mfma_f32_16x16x32_bf16 v[18:21], v[228:231], v[236:239], v[18:21]
	ds_read_b128 v[236:239], v156 offset:256
	s_waitcnt lgkmcnt(12)
	v_alignbyte_b32 v232, v211, v210, v36
	v_alignbyte_b32 v233, v212, v211, v36
	v_alignbyte_b32 v234, v213, v212, v36
	v_alignbyte_b32 v235, v214, v213, v36
	ds_read2_b32 v[210:211], v154 offset0:80 offset1:81
	ds_read2_b32 v[212:213], v154 offset0:82 offset1:83
	ds_read_b32 v214, v154 offset:336
	v_mfma_f32_16x16x32_bf16 v[18:21], v[232:235], v[240:243], v[18:21]
	ds_read_b128 v[240:243], v156 offset:320
	s_waitcnt lgkmcnt(12)
	v_alignbyte_b32 v228, v217, v216, v36
	v_alignbyte_b32 v229, v218, v217, v36
	v_alignbyte_b32 v230, v219, v218, v36
	v_alignbyte_b32 v231, v220, v219, v36
	ds_read2_b32 v[216:217], v154 offset0:96 offset1:97
	ds_read2_b32 v[218:219], v154 offset0:98 offset1:99
	ds_read_b32 v220, v154 offset:400
	v_mfma_f32_16x16x32_bf16 v[18:21], v[228:231], v[244:247], v[18:21]
	ds_read_b128 v[244:247], v156 offset:384
	s_waitcnt lgkmcnt(12)
	v_alignbyte_b32 v232, v223, v222, v36
	v_alignbyte_b32 v233, v224, v223, v36
	v_alignbyte_b32 v234, v225, v224, v36
	v_alignbyte_b32 v235, v226, v225, v36
	ds_read2_b32 v[222:223], v154 offset0:112 offset1:113
	ds_read2_b32 v[224:225], v154 offset0:114 offset1:115
	ds_read_b32 v226, v154 offset:464
	v_mfma_f32_16x16x32_bf16 v[18:21], v[232:235], v[144:147], v[18:21]
	ds_read_b128 v[144:147], v156 offset:448
	s_waitcnt lgkmcnt(12)
	v_alignbyte_b32 v228, v205, v204, v36
	v_alignbyte_b32 v229, v206, v205, v36
	v_alignbyte_b32 v230, v207, v206, v36
	v_alignbyte_b32 v231, v208, v207, v36
	ds_read2_b32 v[204:205], v154 offset0:128 offset1:129
	ds_read2_b32 v[206:207], v154 offset0:130 offset1:131
	ds_read_b32 v208, v154 offset:528
	v_mfma_f32_16x16x32_bf16 v[18:21], v[228:231], v[236:239], v[18:21]
	ds_read_b128 v[236:239], v156 offset:512
	s_waitcnt lgkmcnt(12)
	v_alignbyte_b32 v232, v211, v210, v36
	v_alignbyte_b32 v233, v212, v211, v36
	v_alignbyte_b32 v234, v213, v212, v36
	v_alignbyte_b32 v235, v214, v213, v36
	ds_read2_b32 v[210:211], v154 offset0:144 offset1:145
	ds_read2_b32 v[212:213], v154 offset0:146 offset1:147
	ds_read_b32 v214, v154 offset:592
	v_mfma_f32_16x16x32_bf16 v[18:21], v[232:235], v[240:243], v[18:21]
	ds_read_b128 v[240:243], v156 offset:576
	s_waitcnt lgkmcnt(12)
	v_alignbyte_b32 v228, v217, v216, v36
	v_alignbyte_b32 v229, v218, v217, v36
	v_alignbyte_b32 v230, v219, v218, v36
	v_alignbyte_b32 v231, v220, v219, v36
	ds_read2_b32 v[216:217], v154 offset0:160 offset1:161
	ds_read2_b32 v[218:219], v154 offset0:162 offset1:163
	ds_read_b32 v220, v154 offset:656
	v_mfma_f32_16x16x32_bf16 v[18:21], v[228:231], v[244:247], v[18:21]
	ds_read_b128 v[244:247], v156 offset:640
	s_waitcnt lgkmcnt(12)
	v_alignbyte_b32 v232, v223, v222, v36
	v_alignbyte_b32 v233, v224, v223, v36
	v_alignbyte_b32 v234, v225, v224, v36
	v_alignbyte_b32 v235, v226, v225, v36
	ds_read2_b32 v[222:223], v154 offset0:176 offset1:177
	ds_read2_b32 v[224:225], v154 offset0:178 offset1:179
	ds_read_b32 v226, v154 offset:720
	v_mfma_f32_16x16x32_bf16 v[18:21], v[232:235], v[144:147], v[18:21]
	ds_read_b128 v[144:147], v156 offset:704
	s_waitcnt lgkmcnt(12)
	v_alignbyte_b32 v228, v205, v204, v36
	v_alignbyte_b32 v229, v206, v205, v36
	v_alignbyte_b32 v230, v207, v206, v36
	v_alignbyte_b32 v231, v208, v207, v36
	ds_read2_b32 v[204:205], v154 offset0:192 offset1:193
	ds_read2_b32 v[206:207], v154 offset0:194 offset1:195
	ds_read_b32 v208, v154 offset:784
	v_mfma_f32_16x16x32_bf16 v[18:21], v[228:231], v[236:239], v[18:21]
	ds_read_b128 v[236:239], v156 offset:768
	s_waitcnt lgkmcnt(12)
	v_alignbyte_b32 v232, v211, v210, v36
	v_alignbyte_b32 v233, v212, v211, v36
	v_alignbyte_b32 v234, v213, v212, v36
	v_alignbyte_b32 v235, v214, v213, v36
	ds_read2_b32 v[210:211], v154 offset0:208 offset1:209
	ds_read2_b32 v[212:213], v154 offset0:210 offset1:211
	ds_read_b32 v214, v154 offset:848
	v_mfma_f32_16x16x32_bf16 v[18:21], v[232:235], v[240:243], v[18:21]
	ds_read_b128 v[240:243], v156 offset:832
	s_waitcnt lgkmcnt(12)
	v_alignbyte_b32 v228, v217, v216, v36
	v_alignbyte_b32 v229, v218, v217, v36
	v_alignbyte_b32 v230, v219, v218, v36
	v_alignbyte_b32 v231, v220, v219, v36
	ds_read2_b32 v[216:217], v154 offset0:224 offset1:225
	ds_read2_b32 v[218:219], v154 offset0:226 offset1:227
	ds_read_b32 v220, v154 offset:912
	v_mfma_f32_16x16x32_bf16 v[18:21], v[228:231], v[244:247], v[18:21]
	ds_read_b128 v[244:247], v156 offset:896
	s_waitcnt lgkmcnt(12)
	v_alignbyte_b32 v232, v223, v222, v36
	v_alignbyte_b32 v233, v224, v223, v36
	v_alignbyte_b32 v234, v225, v224, v36
	v_alignbyte_b32 v235, v226, v225, v36
	ds_read2_b32 v[222:223], v154 offset0:240 offset1:241
	ds_read2_b32 v[224:225], v154 offset0:242 offset1:243
	ds_read_b32 v226, v154 offset:976
	v_mfma_f32_16x16x32_bf16 v[18:21], v[232:235], v[144:147], v[18:21]
	ds_read_b128 v[144:147], v156 offset:960
	s_waitcnt lgkmcnt(12)
	v_alignbyte_b32 v228, v205, v204, v36
	v_alignbyte_b32 v229, v206, v205, v36
	v_alignbyte_b32 v230, v207, v206, v36
	v_alignbyte_b32 v231, v208, v207, v36
	s_nop 1
	v_mfma_f32_16x16x32_bf16 v[18:21], v[228:231], v[236:239], v[18:21]
	s_waitcnt lgkmcnt(8)
	v_alignbyte_b32 v232, v211, v210, v36
	v_alignbyte_b32 v233, v212, v211, v36
	v_alignbyte_b32 v234, v213, v212, v36
	v_alignbyte_b32 v235, v214, v213, v36
	s_nop 1
	v_mfma_f32_16x16x32_bf16 v[18:21], v[232:235], v[240:243], v[18:21]
	s_waitcnt lgkmcnt(4)
	v_alignbyte_b32 v228, v217, v216, v36
	v_alignbyte_b32 v229, v218, v217, v36
	v_alignbyte_b32 v230, v219, v218, v36
	v_alignbyte_b32 v231, v220, v219, v36
	s_nop 1
	v_mfma_f32_16x16x32_bf16 v[18:21], v[228:231], v[244:247], v[18:21]
	s_waitcnt lgkmcnt(0)
	v_alignbyte_b32 v232, v223, v222, v36
	v_alignbyte_b32 v233, v224, v223, v36
	v_alignbyte_b32 v234, v225, v224, v36
	v_alignbyte_b32 v235, v226, v225, v36
	s_nop 1
	v_mfma_f32_16x16x32_bf16 v[18:21], v[232:235], v[144:147], v[18:21]
	v_add_u32_e32 v45, s53, v1
	s_movk_i32 s50, 0x600
	v_add_f32_e32 v42, v42, v43
	v_mul_lo_u32 v46, v45, s50
	v_div_scale_f32 v43, s[50:51], v42, v42, 1.0
	v_rcp_f32_e32 v44, v43
	s_nop 0
	v_fma_f32 v47, -v43, v44, 1.0
	v_fmac_f32_e32 v44, v47, v44
	v_div_scale_f32 v47, vcc, 1.0, v42, 1.0
	v_mul_f32_e32 v48, v47, v44
	v_fma_f32 v49, -v43, v48, v47
	v_fmac_f32_e32 v48, v49, v44
	v_fma_f32 v43, -v43, v48, v47
	v_div_fmas_f32 v43, v43, v44, v48
	v_div_fixup_f32 v44, v43, v42, 1.0
	v_lshlrev_b32_e32 v42, 1, v37
	v_add3_u32 v42, s17, v46, v42
	ds_read_b64 v[46:47], v42 offset:512
	v_lshl_add_u32 v43, v45, 9, v38
	ds_read_b64 v[48:49], v43 offset:24576
	s_waitcnt lgkmcnt(1)
	v_and_b32_e32 v53, 0xffff0000, v46
	v_lshlrev_b32_e32 v52, 16, v46
	v_pk_mul_f32 v[52:53], v[110:111], v[52:53] op_sel_hi:[0,1]
	s_waitcnt lgkmcnt(0)
	v_and_b32_e32 v51, 0xffff0000, v48
	v_lshlrev_b32_e32 v50, 16, v48
	v_pk_fma_f32 v[18:19], v[44:45], v[18:19], v[52:53] op_sel_hi:[0,1,1]
	v_pk_mul_f32 v[18:19], v[18:19], v[50:51]
	v_and_b32_e32 v51, 0xffff0000, v49
	v_lshlrev_b32_e32 v50, 16, v49
	v_and_b32_e32 v49, 0xffff0000, v47
	v_lshlrev_b32_e32 v48, 16, v47
	v_pk_mul_f32 v[46:47], v[110:111], v[48:49] op_sel_hi:[0,1]
	v_pk_fma_f32 v[20:21], v[44:45], v[20:21], v[46:47] op_sel_hi:[0,1,1]
	v_pk_mul_f32 v[20:21], v[20:21], v[50:51]
	v_bfe_u32 v45, v19, 16, 1
	v_bfe_u32 v46, v18, 16, 1
	v_add3_u32 v18, v18, v46, s94
	v_add3_u32 v45, v19, v45, s94
	v_cvt_pk_bf16_f32 v20, v20, v21
	v_mov_b32_e32 v19, v20
	v_perm_b32 v18, v45, v18, s95
	ds_write_b64 v42, v[18:19] offset:512
	s_waitcnt vmcnt(1)
	ds_write_b128 v28, v[14:17] offset:32800
	s_and_saveexec_b64 s[50:51], s[44:45]
	ds_write_b128 v28, v[10:13] offset:33824
	s_or_b64 exec, exec, s[50:51]
	v_mov_b32_e32 v14, v27
	v_mov_b32_e32 v15, v27
	s_nop 1
	v_permlane32_swap_b32_e32 v14, v15
	s_or_b32 s50, s52, 1
	s_cmp_gt_u32 s50, 6
	s_waitcnt lgkmcnt(0)
	v_add_f32_e32 v14, v14, v15
	v_mov_b32_e32 v15, v14
	s_nop 1
	v_permlane16_swap_b32_e32 v15, v14
	s_waitcnt lgkmcnt(0)
	v_add_f32_e32 v14, v14, v15
	s_nop 1
	v_mov_b32_dpp v15, v14 row_mirror row_mask:0xf bank_mask:0xf
	s_waitcnt lgkmcnt(0)
	v_add_f32_e32 v14, v14, v15
	s_nop 1
	v_mov_b32_dpp v15, v14 row_half_mirror row_mask:0xf bank_mask:0xf
	s_waitcnt lgkmcnt(0)
	v_add_f32_e32 v14, v14, v15
	s_nop 1
	v_mov_b32_dpp v15, v14 quad_perm:[2,3,0,1] row_mask:0xf bank_mask:0xf
	s_waitcnt lgkmcnt(0)
	v_add_f32_e32 v18, v14, v15
	ds_bpermute_b32 v19, v34, v18
	s_cbranch_scc1 .LBB0_736
	v_add_u32_e32 v16, 4, v26
	v_add_u32_e32 v2, s74, v16
	v_mad_i64_i32 v[14:15], s[50:51], v2, s9, v[22:23]
	global_load_dwordx4 v[2:5], v[14:15], off
	s_and_saveexec_b64 s[50:51], s[44:45]
	s_cbranch_execz .LBB0_733
	global_load_dwordx4 v[6:9], v[14:15], off offset:1024

.LBB0_789:
	ds_write_b128 v70, v[2:5] offset:40992
	ds_write_b128 v70, v[6:9] offset:42016
	ds_write_b128 v70, v[10:13] offset:43040
	ds_write_b128 v70, v[14:17] offset:44064
	s_and_saveexec_b64 s[88:89], s[42:43]
	ds_write_b128 v70, v[18:21] offset:45088
	s_or_b64 exec, exec, s[88:89]
	v_mov_b32_e32 v26, v122
	v_mov_b32_e32 v27, v122
	s_nop 1
	v_permlane32_swap_b32_e32 v26, v27
	v_add_u32_e32 v66, s22, v121
	s_waitcnt lgkmcnt(0)
	v_add_f32_e32 v26, v26, v27
	v_mov_b32_e32 v27, v26
	s_nop 1
	v_permlane16_swap_b32_e32 v27, v26
	s_waitcnt lgkmcnt(0)
	v_add_f32_e32 v26, v26, v27
	s_nop 1
	v_mov_b32_dpp v27, v26 row_mirror row_mask:0xf bank_mask:0xf
	s_waitcnt lgkmcnt(0)
	v_add_f32_e32 v26, v26, v27
	s_nop 1
	v_mov_b32_dpp v27, v26 row_half_mirror row_mask:0xf bank_mask:0xf
	s_waitcnt lgkmcnt(0)
	v_add_f32_e32 v26, v26, v27
	s_nop 1
	v_mov_b32_dpp v27, v26 quad_perm:[2,3,0,1] row_mask:0xf bank_mask:0xf
	s_waitcnt lgkmcnt(0)
	v_add_f32_e32 v87, v26, v27
	v_add_u32_e32 v26, s16, v66
	v_mad_i64_i32 v[42:43], s[88:89], v26, s10, v[62:63]
	global_load_dwordx4 v[26:29], v[42:43], off
	global_load_dwordx4 v[30:33], v[42:43], off offset:1024
	global_load_dwordx4 v[34:37], v[42:43], off offset:2048
	global_load_dwordx4 v[38:41], v[42:43], off offset:3072
	ds_bpermute_b32 v88, v76, v87
	s_and_saveexec_b64 s[88:89], s[42:43]
	s_cbranch_execz .LBB0_793
	v_add_co_u32_e32 v22, vcc, 0x1000, v42
	s_nop 1
	v_addc_co_u32_e32 v23, vcc, 0, v43, vcc
	global_load_dwordx4 v[22:25], v[22:23], off

.Lhl_conv_a:
	s_waitcnt lgkmcnt(9)
	v_alignbyte_b32 v228, v205, v204, v80
	v_alignbyte_b32 v229, v206, v205, v80
	v_alignbyte_b32 v230, v207, v206, v80
	v_alignbyte_b32 v231, v208, v207, v80
	ds_read2_b32 v[204:205], v157 offset0:16 offset1:17
	ds_read2_b32 v[206:207], v157 offset0:18 offset1:19
	ds_read_b32 v208, v157 offset:80
	ds_read_b128 v[240:243], v91 offset:64
	v_mfma_f32_16x16x32_bf16 v[50:53], v[228:231], v[236:239], v[50:53]
	s_waitcnt lgkmcnt(10)
	v_alignbyte_b32 v232, v211, v210, v80
	v_alignbyte_b32 v233, v212, v211, v80
	v_alignbyte_b32 v234, v213, v212, v80
	v_alignbyte_b32 v235, v214, v213, v80
	ds_read2_b32 v[210:211], v156 offset0:16 offset1:17
	ds_read2_b32 v[212:213], v156 offset0:18 offset1:19
	ds_read_b32 v214, v156 offset:80
	v_mfma_f32_16x16x32_bf16 v[54:57], v[232:235], v[236:239], v[54:57]
	s_waitcnt lgkmcnt(10)
	v_alignbyte_b32 v228, v217, v216, v80
	v_alignbyte_b32 v229, v218, v217, v80
	v_alignbyte_b32 v230, v219, v218, v80
	v_alignbyte_b32 v231, v220, v219, v80
	ds_read2_b32 v[216:217], v155 offset0:16 offset1:17
	ds_read2_b32 v[218:219], v155 offset0:18 offset1:19
	ds_read_b32 v220, v155 offset:80
	v_mfma_f32_16x16x32_bf16 v[42:45], v[228:231], v[236:239], v[42:45]
	s_waitcnt lgkmcnt(10)
	v_alignbyte_b32 v232, v223, v222, v80
	v_alignbyte_b32 v233, v224, v223, v80
	v_alignbyte_b32 v234, v225, v224, v80
	v_alignbyte_b32 v235, v226, v225, v80
	ds_read2_b32 v[222:223], v154 offset0:16 offset1:17
	ds_read2_b32 v[224:225], v154 offset0:18 offset1:19
	ds_read_b32 v226, v154 offset:80
	v_mfma_f32_16x16x32_bf16 v[46:49], v[232:235], v[236:239], v[46:49]
	s_waitcnt lgkmcnt(9)
	v_alignbyte_b32 v228, v205, v204, v80
	v_alignbyte_b32 v229, v206, v205, v80
	v_alignbyte_b32 v230, v207, v206, v80
	v_alignbyte_b32 v231, v208, v207, v80
	ds_read2_b32 v[204:205], v157 offset0:32 offset1:33
	ds_read2_b32 v[206:207], v157 offset0:34 offset1:35
	ds_read_b32 v208, v157 offset:144
	ds_read_b128 v[236:239], v91 offset:128
	v_mfma_f32_16x16x32_bf16 v[50:53], v[228:231], v[240:243], v[50:53]
	s_waitcnt lgkmcnt(10)
	v_alignbyte_b32 v232, v211, v210, v80
	v_alignbyte_b32 v233, v212, v211, v80
	v_alignbyte_b32 v234, v213, v212, v80
	v_alignbyte_b32 v235, v214, v213, v80
	ds_read2_b32 v[210:211], v156 offset0:32 offset1:33
	ds_read2_b32 v[212:213], v156 offset0:34 offset1:35
	ds_read_b32 v214, v156 offset:144
	v_mfma_f32_16x16x32_bf16 v[54:57], v[232:235], v[240:243], v[54:57]
	s_waitcnt lgkmcnt(10)
	v_alignbyte_b32 v228, v217, v216, v80
	v_alignbyte_b32 v229, v218, v217, v80
	v_alignbyte_b32 v230, v219, v218, v80
	v_alignbyte_b32 v231, v220, v219, v80
	ds_read2_b32 v[216:217], v155 offset0:32 offset1:33
	ds_read2_b32 v[218:219], v155 offset0:34 offset1:35
	ds_read_b32 v220, v155 offset:144
	v_mfma_f32_16x16x32_bf16 v[42:45], v[228:231], v[240:243], v[42:45]
	s_waitcnt lgkmcnt(10)
	v_alignbyte_b32 v232, v223, v222, v80
	v_alignbyte_b32 v233, v224, v223, v80
	v_alignbyte_b32 v234, v225, v224, v80
	v_alignbyte_b32 v235, v226, v225, v80
	ds_read2_b32 v[222:223], v154 offset0:32 offset1:33
	ds_read2_b32 v[224:225], v154 offset0:34 offset1:35
	ds_read_b32 v226, v154 offset:144
	v_add_u32_e32 v91, 0x80, v91
	v_add_u32_e32 v154, 0x80, v154
	v_add_u32_e32 v155, 0x80, v155
	v_add_u32_e32 v156, 0x80, v156
	v_add_u32_e32 v157, 0x80, v157
	s_add_i32 s22, s22, 64
	s_cmpk_gt_i32 s22, 0x3c0
	v_mfma_f32_16x16x32_bf16 v[46:49], v[232:235], v[240:243], v[46:49]
	s_cbranch_scc0 .Lhl_conv_a
	s_waitcnt lgkmcnt(0)
	v_add_f32_e32 v58, v87, v88
	v_div_scale_f32 v59, s[22:23], v58, v58, 1.0
	v_rcp_f32_e32 v60, v59
	s_nop 0
	v_fma_f32 v61, -v59, v60, 1.0
	v_fmac_f32_e32 v60, v61, v60
	v_div_scale_f32 v61, vcc, 1.0, v58, 1.0
	v_mul_f32_e32 v87, v61, v60
	v_fma_f32 v88, -v59, v87, v61
	v_fmac_f32_e32 v87, v88, v60
	v_fma_f32 v59, -v59, v87, v61
	v_div_fmas_f32 v59, v59, v60, v87
	v_div_fixup_f32 v58, v59, v58, 1.0
	v_lshl_add_u32 v59, v81, 1, v90
	ds_read2st64_b64 v[90:93], v59 offset0:1 offset1:2
	v_lshl_add_u32 v87, v89, 11, v82
	ds_read_b64 v[60:61], v87 offset:24576
	s_waitcnt lgkmcnt(1)
	v_and_b32_e32 v127, 0xffff0000, v90
	v_lshlrev_b32_e32 v126, 16, v90
	v_pk_mul_f32 v[126:127], v[100:101], v[126:127] op_sel_hi:[0,1]
	s_waitcnt lgkmcnt(0)
	v_and_b32_e32 v89, 0xffff0000, v60
	v_lshlrev_b32_e32 v88, 16, v60
	v_pk_fma_f32 v[50:51], v[58:59], v[50:51], v[126:127] op_sel_hi:[0,1,1]
	v_pk_mul_f32 v[50:51], v[50:51], v[88:89]
	v_and_b32_e32 v89, 0xffff0000, v61
	v_lshlrev_b32_e32 v88, 16, v61
	v_and_b32_e32 v61, 0xffff0000, v91
	v_lshlrev_b32_e32 v60, 16, v91
	v_pk_mul_f32 v[60:61], v[100:101], v[60:61] op_sel_hi:[0,1]
	v_pk_fma_f32 v[52:53], v[58:59], v[52:53], v[60:61] op_sel_hi:[0,1,1]
	v_pk_mul_f32 v[52:53], v[52:53], v[88:89]
	v_bfe_u32 v88, v51, 16, 1
	v_bfe_u32 v89, v50, 16, 1
	v_add3_u32 v50, v50, v89, s94
	v_add3_u32 v88, v51, v88, s94
	v_cvt_pk_bf16_f32 v52, v52, v53
	v_mov_b32_e32 v51, v52
	v_perm_b32 v50, v88, v50, s95
	ds_write_b64 v59, v[50:51] offset:512
	ds_read_b64 v[50:51], v87 offset:25088
	v_and_b32_e32 v61, 0xffff0000, v92
	v_lshlrev_b32_e32 v60, 16, v92
	v_pk_mul_f32 v[60:61], v[100:101], v[60:61] op_sel_hi:[0,1]
	v_pk_fma_f32 v[54:55], v[58:59], v[54:55], v[60:61] op_sel_hi:[0,1,1]
	s_waitcnt lgkmcnt(0)
	v_and_b32_e32 v53, 0xffff0000, v50
	v_lshlrev_b32_e32 v52, 16, v50
	v_pk_mul_f32 v[52:53], v[54:55], v[52:53]
	v_and_b32_e32 v55, 0xffff0000, v51
	v_lshlrev_b32_e32 v54, 16, v51
	v_and_b32_e32 v51, 0xffff0000, v93
	v_lshlrev_b32_e32 v50, 16, v93
	v_pk_mul_f32 v[50:51], v[100:101], v[50:51] op_sel_hi:[0,1]
	v_pk_fma_f32 v[50:51], v[58:59], v[56:57], v[50:51] op_sel_hi:[0,1,1]
	v_pk_mul_f32 v[50:51], v[50:51], v[54:55]
	v_cvt_pk_bf16_f32 v52, v52, v53
	v_cvt_pk_bf16_f32 v50, v50, v51
	v_mov_b32_e32 v51, v50
	v_mov_b32_e32 v50, v52
	ds_write_b64 v59, v[50:51] offset:1024
	ds_read2st64_b64 v[50:53], v59 offset0:3 offset1:4
	ds_read_b64 v[54:55], v87 offset:25600
	s_waitcnt lgkmcnt(1)
	v_and_b32_e32 v61, 0xffff0000, v50
	v_lshlrev_b32_e32 v60, 16, v50
	v_pk_mul_f32 v[60:61], v[100:101], v[60:61] op_sel_hi:[0,1]
	s_waitcnt lgkmcnt(0)
	v_and_b32_e32 v57, 0xffff0000, v54
	v_lshlrev_b32_e32 v56, 16, v54
	v_pk_fma_f32 v[42:43], v[58:59], v[42:43], v[60:61] op_sel_hi:[0,1,1]
	v_pk_mul_f32 v[42:43], v[42:43], v[56:57]
	v_and_b32_e32 v57, 0xffff0000, v55
	v_lshlrev_b32_e32 v56, 16, v55
	v_and_b32_e32 v55, 0xffff0000, v51
	v_lshlrev_b32_e32 v54, 16, v51
	v_pk_mul_f32 v[50:51], v[100:101], v[54:55] op_sel_hi:[0,1]
	v_pk_fma_f32 v[44:45], v[58:59], v[44:45], v[50:51] op_sel_hi:[0,1,1]
	v_pk_mul_f32 v[44:45], v[44:45], v[56:57]
	v_bfe_u32 v54, v43, 16, 1
	v_bfe_u32 v55, v42, 16, 1
	v_add3_u32 v42, v42, v55, s94
	v_add3_u32 v54, v43, v54, s94
	v_cvt_pk_bf16_f32 v44, v44, v45
	v_mov_b32_e32 v43, v44
	v_perm_b32 v42, v54, v42, s95
	ds_write_b64 v59, v[42:43] offset:1536
	ds_read_b64 v[42:43], v87 offset:26112
	v_and_b32_e32 v51, 0xffff0000, v52
	v_lshlrev_b32_e32 v50, 16, v52
	v_pk_mul_f32 v[50:51], v[100:101], v[50:51] op_sel_hi:[0,1]
	v_pk_fma_f32 v[46:47], v[58:59], v[46:47], v[50:51] op_sel_hi:[0,1,1]
	s_waitcnt lgkmcnt(0)
	v_and_b32_e32 v45, 0xffff0000, v42
	v_lshlrev_b32_e32 v44, 16, v42
	v_pk_mul_f32 v[44:45], v[46:47], v[44:45]
	v_and_b32_e32 v47, 0xffff0000, v43
	v_lshlrev_b32_e32 v46, 16, v43
	v_and_b32_e32 v43, 0xffff0000, v53
	v_lshlrev_b32_e32 v42, 16, v53
	v_pk_mul_f32 v[42:43], v[100:101], v[42:43] op_sel_hi:[0,1]
	v_pk_fma_f32 v[42:43], v[58:59], v[48:49], v[42:43] op_sel_hi:[0,1,1]
	v_pk_mul_f32 v[42:43], v[42:43], v[46:47]
	v_cvt_pk_bf16_f32 v44, v44, v45
	v_cvt_pk_bf16_f32 v42, v42, v43
	v_mov_b32_e32 v43, v42
	v_mov_b32_e32 v42, v44
	ds_write_b64 v59, v[42:43] offset:2048
	s_waitcnt vmcnt(5)
	ds_write_b128 v70, v[26:29] offset:40992
	s_waitcnt vmcnt(4)
	ds_write_b128 v70, v[30:33] offset:42016
	s_waitcnt vmcnt(3)
	ds_write_b128 v70, v[34:37] offset:43040
	s_waitcnt vmcnt(2)
	ds_write_b128 v70, v[38:41] offset:44064
	s_and_saveexec_b64 s[92:93], s[42:43]
	ds_write_b128 v70, v[22:25] offset:45088
	s_or_b64 exec, exec, s[92:93]
	s_waitcnt vmcnt(1)
	v_mov_b32_e32 v26, v86
	v_mov_b32_e32 v27, v86
	s_nop 1
	v_permlane32_swap_b32_e32 v26, v27
	s_andn2_b64 vcc, exec, s[90:91]
	s_waitcnt lgkmcnt(0)
	v_add_f32_e32 v26, v26, v27
	v_mov_b32_e32 v27, v26
	s_nop 1
	v_permlane16_swap_b32_e32 v27, v26
	s_waitcnt lgkmcnt(0)
	v_add_f32_e32 v26, v26, v27
	s_nop 1
	v_mov_b32_dpp v27, v26 row_mirror row_mask:0xf bank_mask:0xf
	s_waitcnt lgkmcnt(0)
	v_add_f32_e32 v26, v26, v27
	s_nop 1
	v_mov_b32_dpp v27, v26 row_half_mirror row_mask:0xf bank_mask:0xf
	s_waitcnt lgkmcnt(0)
	v_add_f32_e32 v26, v26, v27
	s_nop 1
	v_mov_b32_dpp v27, v26 quad_perm:[2,3,0,1] row_mask:0xf bank_mask:0xf
	s_waitcnt lgkmcnt(0)
	v_add_f32_e32 v46, v26, v27
	ds_bpermute_b32 v47, v76, v46
	s_cbranch_vccnz .LBB0_801
	v_add_u32_e32 v28, 4, v66
	v_add_u32_e32 v2, s74, v28
	v_mad_i64_i32 v[26:27], s[22:23], v2, s10, v[62:63]
	global_load_dwordx4 v[2:5], v[26:27], off
	global_load_dwordx4 v[6:9], v[26:27], off offset:1024
	global_load_dwordx4 v[10:13], v[26:27], off offset:2048
	global_load_dwordx4 v[14:17], v[26:27], off offset:3072
	s_and_saveexec_b64 s[90:91], s[42:43]
	s_cbranch_execz .LBB0_800
	v_add_co_u32_e32 v18, vcc, 0x1000, v26
	s_nop 1
	v_addc_co_u32_e32 v19, vcc, 0, v27, vcc
	global_load_dwordx4 v[18:21], v[18:19], off
